# MoBA: computing waves spread the next-tile LDS writes and next-next-tile global loads through the softmax exp stream instead of one block at interval head
# speedup vs baseline: 1.0136x; 1.0083x over previous
.LBB0_156:
	s_and_b64 vcc, exec, s[8:9]
	s_cbranch_vccz .Lms_inter
	v_mov_b32_e32 v198, v197
	s_nop 1
	v_permlane16_swap_b32_e32 v197, v198
	v_max_f32_e32 v197, v197, v198
	v_mov_b32_e32 v198, v197
	s_nop 1
	v_permlane32_swap_b32_e32 v197, v198
	v_max3_f32 v197, v196, v197, v198
	v_cmp_neq_f32_e32 vcc, s73, v197
	s_nop 1
	v_cndmask_b32_e32 v198, 0, v197, vcc
	v_sub_f32_e32 v196, v196, v198
	v_mul_f32_e32 v199, 0x3e0293ee, v196
	v_mul_f32_e32 v196, 0xbe0293ee, v198
	v_cndmask_b32_e64 v198, v196, v215, s[0:1]
	v_fmamk_f32 v112, v112, 0x3e0293ee, v198
	v_exp_f32_e32 v112, v112
	v_fmamk_f32 v113, v113, 0x3e0293ee, v198
	v_exp_f32_e32 v113, v113
	v_fmamk_f32 v114, v114, 0x3e0293ee, v198
	v_exp_f32_e32 v114, v114
	v_fmamk_f32 v115, v115, 0x3e0293ee, v198
	v_exp_f32_e32 v115, v115
	v_fmamk_f32 v108, v108, 0x3e0293ee, v198
	v_add_f32_e32 v196, 0, v112
	v_exp_f32_e32 v108, v108
	v_fmamk_f32 v109, v109, 0x3e0293ee, v198
	v_add_f32_e32 v196, v113, v196
	v_exp_f32_e32 v109, v109
	v_fmamk_f32 v110, v110, 0x3e0293ee, v198
	v_add_f32_e32 v196, v114, v196
	v_exp_f32_e32 v110, v110
	v_fmamk_f32 v111, v111, 0x3e0293ee, v198
	v_add_f32_e32 v196, v115, v196
	v_exp_f32_e32 v111, v111
	v_fmamk_f32 v104, v104, 0x3e0293ee, v198
	v_add_f32_e32 v196, v108, v196
	v_exp_f32_e32 v104, v104
	v_fmamk_f32 v105, v105, 0x3e0293ee, v198
	v_add_f32_e32 v196, v109, v196
	v_exp_f32_e32 v105, v105
	v_fmamk_f32 v106, v106, 0x3e0293ee, v198
	v_add_f32_e32 v196, v110, v196
	v_exp_f32_e32 v106, v106
	v_fmamk_f32 v107, v107, 0x3e0293ee, v198
	v_add_f32_e32 v196, v111, v196
	v_exp_f32_e32 v107, v107
	v_fmamk_f32 v100, v100, 0x3e0293ee, v198
	v_add_f32_e32 v196, v104, v196
	v_exp_f32_e32 v100, v100
	v_fmamk_f32 v101, v101, 0x3e0293ee, v198
	v_add_f32_e32 v196, v105, v196
	v_exp_f32_e32 v101, v101
	v_fmamk_f32 v102, v102, 0x3e0293ee, v198
	v_add_f32_e32 v196, v106, v196
	v_exp_f32_e32 v102, v102
	v_fmamk_f32 v103, v103, 0x3e0293ee, v198
	v_add_f32_e32 v196, v107, v196
	v_exp_f32_e32 v103, v103
	v_fmamk_f32 v96, v96, 0x3e0293ee, v198
	v_add_f32_e32 v196, v100, v196
	v_exp_f32_e32 v96, v96
	v_fmamk_f32 v97, v97, 0x3e0293ee, v198
	v_add_f32_e32 v196, v101, v196
	v_exp_f32_e32 v97, v97
	v_fmamk_f32 v98, v98, 0x3e0293ee, v198
	v_add_f32_e32 v196, v102, v196
	v_exp_f32_e32 v98, v98
	v_fmamk_f32 v99, v99, 0x3e0293ee, v198
	v_add_f32_e32 v196, v103, v196
	v_exp_f32_e32 v99, v99
	v_fmamk_f32 v92, v92, 0x3e0293ee, v198
	v_add_f32_e32 v196, v96, v196
	v_exp_f32_e32 v92, v92
	v_fmamk_f32 v93, v93, 0x3e0293ee, v198
	v_add_f32_e32 v196, v97, v196
	v_exp_f32_e32 v93, v93
	v_fmamk_f32 v94, v94, 0x3e0293ee, v198
	v_add_f32_e32 v196, v98, v196
	v_exp_f32_e32 v94, v94
	v_fmamk_f32 v95, v95, 0x3e0293ee, v198
	v_add_f32_e32 v196, v99, v196
	v_exp_f32_e32 v95, v95
	v_fmamk_f32 v88, v88, 0x3e0293ee, v198
	v_add_f32_e32 v196, v92, v196
	v_exp_f32_e32 v88, v88
	v_fmamk_f32 v89, v89, 0x3e0293ee, v198
	v_add_f32_e32 v196, v93, v196
	v_exp_f32_e32 v89, v89
	v_fmamk_f32 v90, v90, 0x3e0293ee, v198
	v_add_f32_e32 v196, v94, v196
	v_exp_f32_e32 v90, v90
	v_fmamk_f32 v91, v91, 0x3e0293ee, v198
	v_add_f32_e32 v196, v95, v196
	v_exp_f32_e32 v91, v91
	v_add_f32_e32 v196, v88, v196
	v_add_f32_e32 v196, v89, v196
	v_add_f32_e32 v196, v90, v196
	v_fmamk_f32 v84, v84, 0x3e0293ee, v198
	v_add_f32_e32 v200, v91, v196
	v_exp_f32_e32 v196, v84
	v_fmamk_f32 v85, v85, 0x3e0293ee, v198
	v_exp_f32_e32 v85, v85
	v_fmamk_f32 v86, v86, 0x3e0293ee, v198
	v_exp_f32_e32 v86, v86
	v_fmac_f32_e32 v198, 0x3e0293ee, v87
	v_exp_f32_e32 v87, v198
	v_add_f32_e32 v84, v196, v200
	v_add_f32_e32 v84, v85, v84
	v_add_f32_e32 v84, v86, v84
	v_add_f32_e32 v198, v87, v84
	v_exp_f32_e32 v84, v199
	v_mov_b32_e32 v199, v198
	s_nop 1
	v_permlane16_swap_b32_e32 v198, v199
	v_add_f32_e32 v198, v198, v199
	v_mov_b32_e32 v199, v198
	v_cmp_neq_f32_e32 vcc, 1.0, v84
	s_nop 0
	v_permlane32_swap_b32_e32 v198, v199
	s_cbranch_vccz .LBB0_158

	v_pk_mul_f32 v[82:83], v[82:83], v[84:85] op_sel_hi:[1,0]
	v_pk_mul_f32 v[80:81], v[80:81], v[84:85] op_sel_hi:[1,0]
	v_pk_mul_f32 v[78:79], v[78:79], v[84:85] op_sel_hi:[1,0]
	v_pk_mul_f32 v[76:77], v[76:77], v[84:85] op_sel_hi:[1,0]
	v_pk_mul_f32 v[74:75], v[74:75], v[84:85] op_sel_hi:[1,0]
	v_pk_mul_f32 v[72:73], v[72:73], v[84:85] op_sel_hi:[1,0]
	v_pk_mul_f32 v[70:71], v[70:71], v[84:85] op_sel_hi:[1,0]
	v_pk_mul_f32 v[68:69], v[68:69], v[84:85] op_sel_hi:[1,0]
	v_pk_mul_f32 v[66:67], v[66:67], v[84:85] op_sel_hi:[1,0]
	v_pk_mul_f32 v[64:65], v[64:65], v[84:85] op_sel_hi:[1,0]
	v_pk_mul_f32 v[62:63], v[62:63], v[84:85] op_sel_hi:[1,0]
	v_pk_mul_f32 v[60:61], v[60:61], v[84:85] op_sel_hi:[1,0]
	v_pk_mul_f32 v[58:59], v[58:59], v[84:85] op_sel_hi:[1,0]
	v_pk_mul_f32 v[56:57], v[56:57], v[84:85] op_sel_hi:[1,0]
	v_pk_mul_f32 v[54:55], v[54:55], v[84:85] op_sel_hi:[1,0]
	v_pk_mul_f32 v[52:53], v[52:53], v[84:85] op_sel_hi:[1,0]
	s_branch .LBB0_158
.Lms_inter:
	v_mov_b32_e32 v198, v197
	s_nop 1
	v_permlane16_swap_b32_e32 v197, v198
	v_max_f32_e32 v197, v197, v198
	v_mov_b32_e32 v198, v197
	s_nop 1
	v_permlane32_swap_b32_e32 v197, v198
	v_max3_f32 v197, v196, v197, v198
	v_cmp_neq_f32_e32 vcc, s73, v197
	s_nop 1
	v_cndmask_b32_e32 v198, 0, v197, vcc
	v_sub_f32_e32 v196, v196, v198
	v_mul_f32_e32 v199, 0x3e0293ee, v196
	v_mul_f32_e32 v196, 0xbe0293ee, v198
	v_cndmask_b32_e64 v198, v196, v215, s[0:1]
	v_fmamk_f32 v112, v112, 0x3e0293ee, v198
	v_exp_f32_e32 v112, v112
	s_xor_b32 s87, s15, 1
	v_fmamk_f32 v113, v113, 0x3e0293ee, v198
	v_exp_f32_e32 v113, v113
	s_mul_i32 s87, s87, 0x11000
	v_fmamk_f32 v114, v114, 0x3e0293ee, v198
	v_exp_f32_e32 v114, v114
	s_add_i32 s87, s87, 0
	v_fmamk_f32 v115, v115, 0x3e0293ee, v198
	v_exp_f32_e32 v115, v115
	v_add3_u32 v224, s87, v165, v216
	v_fmamk_f32 v108, v108, 0x3e0293ee, v198
	v_add3_u32 v223, s87, v0, v216
	v_add_f32_e32 v196, 0, v112
	v_exp_f32_e32 v108, v108
	v_add_u32_e32 v225, 0x8800, v224
	v_fmamk_f32 v109, v109, 0x3e0293ee, v198
	v_add_f32_e32 v196, v113, v196
	s_waitcnt vmcnt(7)
	v_exp_f32_e32 v109, v109
	v_fmamk_f32 v110, v110, 0x3e0293ee, v198
	ds_write_b128 v223, v[4:7]
	v_add_f32_e32 v196, v114, v196
	s_waitcnt vmcnt(6)
	v_exp_f32_e32 v110, v110
	v_fmamk_f32 v111, v111, 0x3e0293ee, v198
	ds_write2_b64 v225, v[8:9], v[10:11] offset1:2
	v_add_f32_e32 v196, v115, v196
	v_exp_f32_e32 v111, v111
	s_waitcnt vmcnt(5)
	v_fmamk_f32 v104, v104, 0x3e0293ee, v198
	v_add_f32_e32 v196, v108, v196
	ds_write_b128 v223, v[12:15] offset:8704
	v_exp_f32_e32 v104, v104
	v_add_u32_e32 v225, 0xa800, v224
	v_fmamk_f32 v105, v105, 0x3e0293ee, v198
	v_add_f32_e32 v196, v109, v196
	s_waitcnt vmcnt(4)
	v_exp_f32_e32 v105, v105
	v_fmamk_f32 v106, v106, 0x3e0293ee, v198
	ds_write2_b64 v225, v[16:17], v[18:19] offset0:64 offset1:66
	v_add_f32_e32 v196, v110, v196
	v_exp_f32_e32 v106, v106
	s_waitcnt vmcnt(3)
	v_fmamk_f32 v107, v107, 0x3e0293ee, v198
	ds_write_b128 v223, v[20:23] offset:17408
	v_add_f32_e32 v196, v111, v196
	v_exp_f32_e32 v107, v107
	v_add_u32_e32 v225, 0xc800, v224
	v_fmamk_f32 v100, v100, 0x3e0293ee, v198
	v_add_f32_e32 v196, v104, v196
	s_waitcnt vmcnt(2)
	v_exp_f32_e32 v100, v100
	v_fmamk_f32 v101, v101, 0x3e0293ee, v198
	ds_write2_b64 v225, v[24:25], v[26:27] offset0:128 offset1:130
	v_add_f32_e32 v196, v105, v196
	s_waitcnt vmcnt(1)
	v_exp_f32_e32 v101, v101
	v_fmamk_f32 v102, v102, 0x3e0293ee, v198
	ds_write_b128 v223, v[28:31] offset:26112
	v_add_f32_e32 v196, v106, v196
	v_exp_f32_e32 v102, v102
	v_add_u32_e32 v223, 0xe800, v224
	v_fmamk_f32 v103, v103, 0x3e0293ee, v198
	v_add_f32_e32 v196, v107, v196
	s_waitcnt vmcnt(0)
	v_exp_f32_e32 v103, v103
	ds_write2_b64 v223, v[32:33], v[34:35] offset0:192 offset1:194
	s_andn2_b64 vcc, exec, s[80:81]
	s_cbranch_vccnz .Lms_t2plain
	v_fmamk_f32 v96, v96, 0x3e0293ee, v198
	v_add_f32_e32 v196, v100, v196
	s_lshr_b32 s82, s14, 1
	v_exp_f32_e32 v96, v96
	s_sub_i32 s82, s47, s82
	v_fmamk_f32 v97, v97, 0x3e0293ee, v198
	s_lshl_b32 s83, s14, 7
	v_add_f32_e32 v196, v101, v196
	s_lshl_b32 s82, s82, 8
	v_exp_f32_e32 v97, v97
	s_and_b32 s83, s83, 0x80
	v_fmamk_f32 v98, v98, 0x3e0293ee, v198
	s_or_b32 s82, s82, s83
	v_add_f32_e32 v196, v102, v196
	s_ashr_i32 s83, s82, 31
	v_exp_f32_e32 v98, v98
	v_fmamk_f32 v99, v99, 0x3e0293ee, v198
	v_lshl_add_u64 v[4:5], v[140:141], 0, s[82:83]
	v_add_f32_e32 v196, v103, v196
	v_mov_b64_e32 v[6:7], s[88:89]
	v_exp_f32_e32 v99, v99
	v_lshl_add_u64 v[28:29], s[82:83], 1, v[118:119]
	v_fmamk_f32 v92, v92, 0x3e0293ee, v198
	v_mad_u64_u32 v[6:7], s[82:83], v4, s72, v[6:7]
	v_add_f32_e32 v196, v96, v196
	v_mad_i32_i24 v7, v5, s72, v7
	v_exp_f32_e32 v92, v92
	v_lshl_add_u64 v[4:5], v[6:7], 0, s[20:21]
	v_fmamk_f32 v93, v93, 0x3e0293ee, v198
	v_lshl_add_u64 v[30:31], v[4:5], 0, v[2:3]
	v_add_f32_e32 v196, v97, v196
	v_add_co_u32_e32 v4, vcc, s3, v30
	v_exp_f32_e32 v93, v93
	v_fmamk_f32 v94, v94, 0x3e0293ee, v198
	s_mov_b32 s82, 0x3d000
	v_add_f32_e32 v196, v98, v196
	s_nop 0
	v_exp_f32_e32 v94, v94
	v_addc_co_u32_e32 v5, vcc, 0, v31, vcc
	v_fmamk_f32 v95, v95, 0x3e0293ee, v198
	v_add_co_u32_e32 v12, vcc, s82, v30
	v_add_f32_e32 v196, v99, v196
	v_lshl_add_u64 v[8:9], v[28:29], 0, v[146:147]
	v_exp_f32_e32 v95, v95
	s_nop 0
	v_fmamk_f32 v88, v88, 0x3e0293ee, v198
	v_addc_co_u32_e32 v13, vcc, 0, v31, vcc
	v_add_f32_e32 v196, v92, v196
	v_add_co_u32_e32 v20, vcc, 0x79000, v30
	v_exp_f32_e32 v88, v88
	v_fmamk_f32 v89, v89, 0x3e0293ee, v198
	v_lshl_add_u64 v[16:17], v[28:29], 0, v[148:149]
	v_add_f32_e32 v196, v93, v196
	s_nop 0
	v_exp_f32_e32 v89, v89
	v_addc_co_u32_e32 v21, vcc, 0, v31, vcc
	v_fmamk_f32 v90, v90, 0x3e0293ee, v198
	v_add_co_u32_e32 v30, vcc, 0xb5000, v30
	v_add_f32_e32 v196, v94, v196
	v_lshl_add_u64 v[24:25], v[28:29], 0, v[150:151]
	v_exp_f32_e32 v90, v90
	s_nop 0
	v_fmamk_f32 v91, v91, 0x3e0293ee, v198
	v_addc_co_u32_e32 v31, vcc, 0, v31, vcc
	v_add_f32_e32 v196, v95, v196
	v_exp_f32_e32 v91, v91
	v_lshl_add_u64 v[32:33], v[28:29], 0, v[152:153]
	v_add_f32_e32 v196, v88, v196
	global_load_dwordx4 v[4:7], v[4:5], off offset:1024
	v_add_f32_e32 v196, v89, v196
	s_nop 0
	v_add_f32_e32 v196, v90, v196
	global_load_dwordx4 v[8:11], v[8:9], off
	v_fmamk_f32 v84, v84, 0x3e0293ee, v198
	s_nop 0
	v_add_f32_e32 v200, v91, v196
	global_load_dwordx4 v[12:15], v[12:13], off offset:1024
	v_exp_f32_e32 v196, v84
	s_nop 0
	v_fmamk_f32 v85, v85, 0x3e0293ee, v198
	global_load_dwordx4 v[16:19], v[16:17], off
	v_exp_f32_e32 v85, v85
	v_fmamk_f32 v86, v86, 0x3e0293ee, v198
	s_nop 0
	v_exp_f32_e32 v86, v86
	global_load_dwordx4 v[20:23], v[20:21], off offset:1024
	v_fmac_f32_e32 v198, 0x3e0293ee, v87
	s_nop 0
	v_exp_f32_e32 v87, v198
	global_load_dwordx4 v[24:27], v[24:25], off
	v_add_f32_e32 v84, v196, v200
	s_nop 0
	v_add_f32_e32 v84, v85, v84
	global_load_dwordx4 v[28:31], v[30:31], off offset:1024
	v_add_f32_e32 v84, v86, v84
	s_nop 0
	v_add_f32_e32 v198, v87, v84
	global_load_dwordx4 v[32:35], v[32:33], off
	s_branch .Lms_join
.Lms_t2plain:
	v_fmamk_f32 v96, v96, 0x3e0293ee, v198
	v_add_f32_e32 v196, v100, v196
	v_exp_f32_e32 v96, v96
	v_fmamk_f32 v97, v97, 0x3e0293ee, v198
	v_add_f32_e32 v196, v101, v196
	v_exp_f32_e32 v97, v97
	v_fmamk_f32 v98, v98, 0x3e0293ee, v198
	v_add_f32_e32 v196, v102, v196
	v_exp_f32_e32 v98, v98
	v_fmamk_f32 v99, v99, 0x3e0293ee, v198
	v_add_f32_e32 v196, v103, v196
	v_exp_f32_e32 v99, v99
	v_fmamk_f32 v92, v92, 0x3e0293ee, v198
	v_add_f32_e32 v196, v96, v196
	v_exp_f32_e32 v92, v92
	v_fmamk_f32 v93, v93, 0x3e0293ee, v198
	v_add_f32_e32 v196, v97, v196
	v_exp_f32_e32 v93, v93
	v_fmamk_f32 v94, v94, 0x3e0293ee, v198
	v_add_f32_e32 v196, v98, v196
	v_exp_f32_e32 v94, v94
	v_fmamk_f32 v95, v95, 0x3e0293ee, v198
	v_add_f32_e32 v196, v99, v196
	v_exp_f32_e32 v95, v95
	v_fmamk_f32 v88, v88, 0x3e0293ee, v198
	v_add_f32_e32 v196, v92, v196
	v_exp_f32_e32 v88, v88
	v_fmamk_f32 v89, v89, 0x3e0293ee, v198
	v_add_f32_e32 v196, v93, v196
	v_exp_f32_e32 v89, v89
	v_fmamk_f32 v90, v90, 0x3e0293ee, v198
	v_add_f32_e32 v196, v94, v196
	v_exp_f32_e32 v90, v90
	v_fmamk_f32 v91, v91, 0x3e0293ee, v198
	v_add_f32_e32 v196, v95, v196
	v_exp_f32_e32 v91, v91
	v_add_f32_e32 v196, v88, v196
	v_add_f32_e32 v196, v89, v196
	v_add_f32_e32 v196, v90, v196
	v_fmamk_f32 v84, v84, 0x3e0293ee, v198
	v_add_f32_e32 v200, v91, v196
	v_exp_f32_e32 v196, v84
	v_fmamk_f32 v85, v85, 0x3e0293ee, v198
	v_exp_f32_e32 v85, v85
	v_fmamk_f32 v86, v86, 0x3e0293ee, v198
	v_exp_f32_e32 v86, v86
	v_fmac_f32_e32 v198, 0x3e0293ee, v87
	v_exp_f32_e32 v87, v198
	v_add_f32_e32 v84, v196, v200
	v_add_f32_e32 v84, v85, v84
	v_add_f32_e32 v84, v86, v84
	v_add_f32_e32 v198, v87, v84
.Lms_join:
	v_exp_f32_e32 v84, v199
	v_mov_b32_e32 v199, v198
	s_nop 1
	v_permlane16_swap_b32_e32 v198, v199
	v_add_f32_e32 v198, v198, v199
	v_mov_b32_e32 v199, v198
	v_cmp_neq_f32_e32 vcc, 1.0, v84
	s_nop 0
	v_permlane32_swap_b32_e32 v198, v199
	s_cbranch_vccz .LBB0_158

	v_pk_mul_f32 v[82:83], v[82:83], v[84:85] op_sel_hi:[1,0]
	v_pk_mul_f32 v[80:81], v[80:81], v[84:85] op_sel_hi:[1,0]
	v_pk_mul_f32 v[78:79], v[78:79], v[84:85] op_sel_hi:[1,0]
	v_pk_mul_f32 v[76:77], v[76:77], v[84:85] op_sel_hi:[1,0]
	v_pk_mul_f32 v[74:75], v[74:75], v[84:85] op_sel_hi:[1,0]
	v_pk_mul_f32 v[72:73], v[72:73], v[84:85] op_sel_hi:[1,0]
	v_pk_mul_f32 v[70:71], v[70:71], v[84:85] op_sel_hi:[1,0]
	v_pk_mul_f32 v[68:69], v[68:69], v[84:85] op_sel_hi:[1,0]
	v_pk_mul_f32 v[66:67], v[66:67], v[84:85] op_sel_hi:[1,0]
	v_pk_mul_f32 v[64:65], v[64:65], v[84:85] op_sel_hi:[1,0]
	v_pk_mul_f32 v[62:63], v[62:63], v[84:85] op_sel_hi:[1,0]
	v_pk_mul_f32 v[60:61], v[60:61], v[84:85] op_sel_hi:[1,0]
	v_pk_mul_f32 v[58:59], v[58:59], v[84:85] op_sel_hi:[1,0]
	v_pk_mul_f32 v[56:57], v[56:57], v[84:85] op_sel_hi:[1,0]
	v_pk_mul_f32 v[54:55], v[54:55], v[84:85] op_sel_hi:[1,0]
	v_pk_mul_f32 v[52:53], v[52:53], v[84:85] op_sel_hi:[1,0]
